# r2 + barrier between the last K-slice LDS reads and the output staging in the down-projection GEMM tiles (closes a latent LDS race)
# baseline (speedup 1.0000x reference)
; #define G_LOADA(kt_) { _Pragma("unroll") for (int i = 0; i < 4; ++i) ra[i] = al(lrow + 64 * i, (kt_) * 64 + lck * 8); }
; #define G_LOADB(kt_) { _Pragma("unroll") for (int i = 0; i < 4; ++i) rb[i] = bl(lrow + 64 * i, (kt_) * 64 + lck * 8); }
; #define G_STOREA(buf_) { bf16_t* nA = sA + (buf_) * 256 * GLD; _Pragma("unroll") for (int i = 0; i < 4; ++i) *(u32x4*)(nA + (lrow + 64 * i) * GLD + lck * 8) = ra[i]; }
; #define G_STOREB(buf_) { bf16_t* nB = sB + (buf_) * 256 * GLD; _Pragma("unroll") for (int i = 0; i < 4; ++i) *(u32x4*)(nB + (lrow + 64 * i) * GLD + lck * 8) = rb[i]; }
; template <class AL, class BL, class EP>
; DI void gemm_tile256(AL al, BL bl, EP ep, int K, char* smem) {
;     ...
;   G_LOADA(0); G_LOADB(0);
;   __syncthreads();
;   G_STOREA(0); G_STOREB(0);
;   if (KT > 1) G_LOADB(1);
;   __syncthreads();
;   for (int kt = 0; kt < KT; kt += 2) {
;     G_STEP(0, kt);
;     if (kt + 1 >= KT) break;
;     G_STEP(1, kt + 1);
;   }
.Lgk_ph7_loop:
	s_waitcnt lgkmcnt(0)
	v_mfma_f32_32x32x16_bf16 v[112:127], v[184:187], v[132:135], v[112:127]
	ds_read_b128 v[192:195], v205
	ds_read_b128 v[148:151], v130
	v_mfma_f32_32x32x16_bf16 v[96:111], v[188:191], v[132:135], v[96:111]
	ds_read_b128 v[208:211], v205 offset:2048
	ds_read_b128 v[152:155], v130 offset:2048
	v_mfma_f32_32x32x16_bf16 v[80:95], v[184:187], v[136:139], v[80:95]
	ds_read_b128 v[156:159], v130 offset:4096
	ds_read_b128 v[180:183], v130 offset:6144
	v_mfma_f32_32x32x16_bf16 v[64:79], v[188:191], v[136:139], v[64:79]
	s_add_u32 m0, s29, 0x22000
	s_nop 0
	global_load_lds_dwordx4 v[220:221], off
	v_lshl_add_u64 v[220:221], v[220:221], 0, s[6:7]
	v_mfma_f32_32x32x16_bf16 v[48:63], v[184:187], v[140:143], v[48:63]
	v_mfma_f32_32x32x16_bf16 v[32:47], v[188:191], v[140:143], v[32:47]
	v_mfma_f32_32x32x16_bf16 v[16:31], v[184:187], v[144:147], v[16:31]
	v_mfma_f32_32x32x16_bf16 v[0:15], v[188:191], v[144:147], v[0:15]
	s_add_u32 m0, s29, 0x26000
	s_nop 0
	global_load_lds_dwordx4 v[224:225], off
	v_lshl_add_u64 v[224:225], v[224:225], 0, s[6:7]
	s_waitcnt lgkmcnt(0)
	s_waitcnt vmcnt(12)
	s_barrier
	s_waitcnt lgkmcnt(0)
	v_mfma_f32_32x32x16_bf16 v[112:127], v[192:195], v[148:151], v[112:127]
	ds_read_b128 v[184:187], v131 offset:32768
	ds_read_b128 v[132:135], v128 offset:32768
	v_mfma_f32_32x32x16_bf16 v[96:111], v[208:211], v[148:151], v[96:111]
	ds_read_b128 v[188:191], v131 offset:34816
	ds_read_b128 v[136:139], v128 offset:34816
	v_mfma_f32_32x32x16_bf16 v[80:95], v[192:195], v[152:155], v[80:95]
	ds_read_b128 v[140:143], v128 offset:36864
	ds_read_b128 v[144:147], v128 offset:38912
	v_mfma_f32_32x32x16_bf16 v[64:79], v[208:211], v[152:155], v[64:79]
	s_add_u32 m0, s29, 0x0
	s_nop 0
	global_load_lds_dwordx4 v[218:219], off
	v_lshl_add_u64 v[218:219], v[218:219], 0, s[6:7]
	v_mfma_f32_32x32x16_bf16 v[48:63], v[192:195], v[156:159], v[48:63]
	v_mfma_f32_32x32x16_bf16 v[32:47], v[208:211], v[156:159], v[32:47]
	v_mfma_f32_32x32x16_bf16 v[16:31], v[192:195], v[180:183], v[16:31]
	v_mfma_f32_32x32x16_bf16 v[0:15], v[208:211], v[180:183], v[0:15]
	s_add_u32 m0, s29, 0x4000
	s_nop 0
	global_load_lds_dwordx4 v[222:223], off
	v_lshl_add_u64 v[222:223], v[222:223], 0, s[6:7]
	s_waitcnt lgkmcnt(0)
	v_mfma_f32_32x32x16_bf16 v[112:127], v[184:187], v[132:135], v[112:127]
	ds_read_b128 v[192:195], v205 offset:32768
	ds_read_b128 v[148:151], v130 offset:32768
	v_mfma_f32_32x32x16_bf16 v[96:111], v[188:191], v[132:135], v[96:111]
	ds_read_b128 v[208:211], v205 offset:34816
	ds_read_b128 v[152:155], v130 offset:34816
	v_mfma_f32_32x32x16_bf16 v[80:95], v[184:187], v[136:139], v[80:95]
	ds_read_b128 v[156:159], v130 offset:36864
	ds_read_b128 v[180:183], v130 offset:38912
	v_mfma_f32_32x32x16_bf16 v[64:79], v[188:191], v[136:139], v[64:79]
	s_add_u32 m0, s29, 0x2000
	s_nop 0
	global_load_lds_dwordx4 v[220:221], off
	v_lshl_add_u64 v[220:221], v[220:221], 0, s[6:7]
	v_mfma_f32_32x32x16_bf16 v[48:63], v[184:187], v[140:143], v[48:63]
	v_mfma_f32_32x32x16_bf16 v[32:47], v[188:191], v[140:143], v[32:47]
	v_mfma_f32_32x32x16_bf16 v[16:31], v[184:187], v[144:147], v[16:31]
	v_mfma_f32_32x32x16_bf16 v[0:15], v[188:191], v[144:147], v[0:15]
	s_add_u32 m0, s29, 0x6000
	s_nop 0
	global_load_lds_dwordx4 v[224:225], off
	v_lshl_add_u64 v[224:225], v[224:225], 0, s[6:7]
	s_waitcnt lgkmcnt(0)
	s_waitcnt vmcnt(12)
	s_barrier
	s_waitcnt lgkmcnt(0)
	v_mfma_f32_32x32x16_bf16 v[112:127], v[192:195], v[148:151], v[112:127]
	ds_read_b128 v[184:187], v212
	ds_read_b128 v[132:135], v206
	v_mfma_f32_32x32x16_bf16 v[96:111], v[208:211], v[148:151], v[96:111]
	ds_read_b128 v[188:191], v212 offset:2048
	ds_read_b128 v[136:139], v206 offset:2048
	v_mfma_f32_32x32x16_bf16 v[80:95], v[192:195], v[152:155], v[80:95]
	ds_read_b128 v[140:143], v206 offset:4096
	ds_read_b128 v[144:147], v206 offset:6144
	v_mfma_f32_32x32x16_bf16 v[64:79], v[208:211], v[152:155], v[64:79]
	s_add_u32 m0, s29, 0x8000
	s_nop 0
	global_load_lds_dwordx4 v[218:219], off
	v_lshl_add_u64 v[218:219], v[218:219], 0, s[6:7]
	v_mfma_f32_32x32x16_bf16 v[48:63], v[192:195], v[156:159], v[48:63]
	v_mfma_f32_32x32x16_bf16 v[32:47], v[208:211], v[156:159], v[32:47]
	v_mfma_f32_32x32x16_bf16 v[16:31], v[192:195], v[180:183], v[16:31]
	v_mfma_f32_32x32x16_bf16 v[0:15], v[208:211], v[180:183], v[0:15]
	s_add_u32 m0, s29, 0xc000
	s_nop 0
	global_load_lds_dwordx4 v[222:223], off
	v_lshl_add_u64 v[222:223], v[222:223], 0, s[6:7]
	s_waitcnt lgkmcnt(0)
	v_mfma_f32_32x32x16_bf16 v[112:127], v[184:187], v[132:135], v[112:127]
	ds_read_b128 v[192:195], v213
	ds_read_b128 v[148:151], v207
	v_mfma_f32_32x32x16_bf16 v[96:111], v[188:191], v[132:135], v[96:111]
	ds_read_b128 v[208:211], v213 offset:2048
	ds_read_b128 v[152:155], v207 offset:2048
	v_mfma_f32_32x32x16_bf16 v[80:95], v[184:187], v[136:139], v[80:95]
	ds_read_b128 v[156:159], v207 offset:4096
	ds_read_b128 v[180:183], v207 offset:6144
	v_mfma_f32_32x32x16_bf16 v[64:79], v[188:191], v[136:139], v[64:79]
	s_add_u32 m0, s29, 0xa000
	s_nop 0
	global_load_lds_dwordx4 v[220:221], off
	v_lshl_add_u64 v[220:221], v[220:221], 0, s[6:7]
	v_mfma_f32_32x32x16_bf16 v[48:63], v[184:187], v[140:143], v[48:63]
	v_mfma_f32_32x32x16_bf16 v[32:47], v[188:191], v[140:143], v[32:47]
	v_mfma_f32_32x32x16_bf16 v[16:31], v[184:187], v[144:147], v[16:31]
	v_mfma_f32_32x32x16_bf16 v[0:15], v[188:191], v[144:147], v[0:15]
	s_add_u32 m0, s29, 0xe000
	s_nop 0
	global_load_lds_dwordx4 v[224:225], off
	v_lshl_add_u64 v[224:225], v[224:225], 0, s[6:7]
	s_waitcnt lgkmcnt(0)
	s_waitcnt vmcnt(12)
	s_barrier
; #define G_LOADA(kt_) { _Pragma("unroll") for (int i = 0; i < 4; ++i) ra[i] = al(lrow + 64 * i, (kt_) * 64 + lck * 8); }
; #define G_LOADB(kt_) { _Pragma("unroll") for (int i = 0; i < 4; ++i) rb[i] = bl(lrow + 64 * i, (kt_) * 64 + lck * 8); }
; #define G_STOREA(buf_) { bf16_t* nA = sA + (buf_) * 256 * GLD; _Pragma("unroll") for (int i = 0; i < 4; ++i) *(u32x4*)(nA + (lrow + 64 * i) * GLD + lck * 8) = ra[i]; }
; #define G_STOREB(buf_) { bf16_t* nB = sB + (buf_) * 256 * GLD; _Pragma("unroll") for (int i = 0; i < 4; ++i) *(u32x4*)(nB + (lrow + 64 * i) * GLD + lck * 8) = rb[i]; }
; template <class AL, class BL, class EP>
; DI void gemm_tile256(AL al, BL bl, EP ep, int K, char* smem) {
;     ...
;   G_LOADA(0); G_LOADB(0);
;   __syncthreads();
;   G_STOREA(0); G_STOREB(0);
;   if (KT > 1) G_LOADB(1);
;   __syncthreads();
;   for (int kt = 0; kt < KT; kt += 2) {
;     G_STEP(0, kt);
;     if (kt + 1 >= KT) break;
;     G_STEP(1, kt + 1);
;   }
	s_waitcnt lgkmcnt(0)
	v_mfma_f32_32x32x16_bf16 v[112:127], v[192:195], v[148:151], v[112:127]
	ds_read_b128 v[184:187], v212 offset:32768
	ds_read_b128 v[132:135], v206 offset:32768
	v_mfma_f32_32x32x16_bf16 v[96:111], v[208:211], v[148:151], v[96:111]
	ds_read_b128 v[188:191], v212 offset:34816
	ds_read_b128 v[136:139], v206 offset:34816
	v_mfma_f32_32x32x16_bf16 v[80:95], v[192:195], v[152:155], v[80:95]
	ds_read_b128 v[140:143], v206 offset:36864
	ds_read_b128 v[144:147], v206 offset:38912
	v_mfma_f32_32x32x16_bf16 v[64:79], v[208:211], v[152:155], v[64:79]
	s_add_u32 m0, s29, 0x10000
	s_nop 0
	global_load_lds_dwordx4 v[218:219], off
	v_lshl_add_u64 v[218:219], v[218:219], 0, s[6:7]
	v_mfma_f32_32x32x16_bf16 v[48:63], v[192:195], v[156:159], v[48:63]
	v_mfma_f32_32x32x16_bf16 v[32:47], v[208:211], v[156:159], v[32:47]
	v_mfma_f32_32x32x16_bf16 v[16:31], v[192:195], v[180:183], v[16:31]
	v_mfma_f32_32x32x16_bf16 v[0:15], v[208:211], v[180:183], v[0:15]
	s_add_u32 m0, s29, 0x14000
	s_nop 0
	global_load_lds_dwordx4 v[222:223], off
	v_lshl_add_u64 v[222:223], v[222:223], 0, s[6:7]
	s_waitcnt lgkmcnt(0)
	v_mfma_f32_32x32x16_bf16 v[112:127], v[184:187], v[132:135], v[112:127]
	ds_read_b128 v[192:195], v213 offset:32768
	ds_read_b128 v[148:151], v207 offset:32768
	v_mfma_f32_32x32x16_bf16 v[96:111], v[188:191], v[132:135], v[96:111]
	ds_read_b128 v[208:211], v213 offset:34816
	ds_read_b128 v[152:155], v207 offset:34816
	v_mfma_f32_32x32x16_bf16 v[80:95], v[184:187], v[136:139], v[80:95]
	ds_read_b128 v[156:159], v207 offset:36864
	ds_read_b128 v[180:183], v207 offset:38912
	v_mfma_f32_32x32x16_bf16 v[64:79], v[188:191], v[136:139], v[64:79]
	s_add_u32 m0, s29, 0x12000
	s_nop 0
	global_load_lds_dwordx4 v[220:221], off
	v_lshl_add_u64 v[220:221], v[220:221], 0, s[6:7]
	v_mfma_f32_32x32x16_bf16 v[48:63], v[184:187], v[140:143], v[48:63]
	v_mfma_f32_32x32x16_bf16 v[32:47], v[188:191], v[140:143], v[32:47]
	v_mfma_f32_32x32x16_bf16 v[16:31], v[184:187], v[144:147], v[16:31]
	v_mfma_f32_32x32x16_bf16 v[0:15], v[188:191], v[144:147], v[0:15]
	s_add_u32 m0, s29, 0x16000
	s_nop 0
	global_load_lds_dwordx4 v[224:225], off
	v_lshl_add_u64 v[224:225], v[224:225], 0, s[6:7]
	s_waitcnt lgkmcnt(0)
	s_waitcnt vmcnt(12)
	s_barrier
	s_waitcnt lgkmcnt(0)
	v_mfma_f32_32x32x16_bf16 v[112:127], v[192:195], v[148:151], v[112:127]
	ds_read_b128 v[184:187], v216
	ds_read_b128 v[132:135], v214
	v_mfma_f32_32x32x16_bf16 v[96:111], v[208:211], v[148:151], v[96:111]
	ds_read_b128 v[188:191], v216 offset:2048
	ds_read_b128 v[136:139], v214 offset:2048
	v_mfma_f32_32x32x16_bf16 v[80:95], v[192:195], v[152:155], v[80:95]
	ds_read_b128 v[140:143], v214 offset:4096
	ds_read_b128 v[144:147], v214 offset:6144
	v_mfma_f32_32x32x16_bf16 v[64:79], v[208:211], v[152:155], v[64:79]
	s_add_u32 m0, s29, 0x18000
	s_nop 0
	global_load_lds_dwordx4 v[218:219], off
	v_lshl_add_u64 v[218:219], v[218:219], 0, s[6:7]
	v_mfma_f32_32x32x16_bf16 v[48:63], v[192:195], v[156:159], v[48:63]
	v_mfma_f32_32x32x16_bf16 v[32:47], v[208:211], v[156:159], v[32:47]
	v_mfma_f32_32x32x16_bf16 v[16:31], v[192:195], v[180:183], v[16:31]
	v_mfma_f32_32x32x16_bf16 v[0:15], v[208:211], v[180:183], v[0:15]
	s_add_u32 m0, s29, 0x1c000
	s_nop 0
	global_load_lds_dwordx4 v[222:223], off
	v_lshl_add_u64 v[222:223], v[222:223], 0, s[6:7]
	s_waitcnt lgkmcnt(0)
	v_mfma_f32_32x32x16_bf16 v[112:127], v[184:187], v[132:135], v[112:127]
	ds_read_b128 v[192:195], v217
	ds_read_b128 v[148:151], v215
	v_mfma_f32_32x32x16_bf16 v[96:111], v[188:191], v[132:135], v[96:111]
	ds_read_b128 v[208:211], v217 offset:2048
	ds_read_b128 v[152:155], v215 offset:2048
	v_mfma_f32_32x32x16_bf16 v[80:95], v[184:187], v[136:139], v[80:95]
	ds_read_b128 v[156:159], v215 offset:4096
	ds_read_b128 v[180:183], v215 offset:6144
	v_mfma_f32_32x32x16_bf16 v[64:79], v[188:191], v[136:139], v[64:79]
	s_add_u32 m0, s29, 0x1a000
	s_nop 0
	global_load_lds_dwordx4 v[220:221], off
	v_lshl_add_u64 v[220:221], v[220:221], 0, s[6:7]
	v_mfma_f32_32x32x16_bf16 v[48:63], v[184:187], v[140:143], v[48:63]
	v_mfma_f32_32x32x16_bf16 v[32:47], v[188:191], v[140:143], v[32:47]
	v_mfma_f32_32x32x16_bf16 v[16:31], v[184:187], v[144:147], v[16:31]
	v_mfma_f32_32x32x16_bf16 v[0:15], v[188:191], v[144:147], v[0:15]
	s_add_u32 m0, s29, 0x1e000
	s_nop 0
	global_load_lds_dwordx4 v[224:225], off
	v_lshl_add_u64 v[224:225], v[224:225], 0, s[6:7]
	s_waitcnt lgkmcnt(0)
	s_waitcnt vmcnt(12)
	s_barrier
	s_waitcnt lgkmcnt(0)
	v_mfma_f32_32x32x16_bf16 v[112:127], v[192:195], v[148:151], v[112:127]
	ds_read_b128 v[184:187], v131
	ds_read_b128 v[132:135], v128
	v_mfma_f32_32x32x16_bf16 v[96:111], v[208:211], v[148:151], v[96:111]
	ds_read_b128 v[188:191], v131 offset:2048
	ds_read_b128 v[136:139], v128 offset:2048
	v_mfma_f32_32x32x16_bf16 v[80:95], v[192:195], v[152:155], v[80:95]
	ds_read_b128 v[140:143], v128 offset:4096
	ds_read_b128 v[144:147], v128 offset:6144
	v_mfma_f32_32x32x16_bf16 v[64:79], v[208:211], v[152:155], v[64:79]
	s_add_u32 m0, s29, 0x20000
	s_nop 0
	global_load_lds_dwordx4 v[218:219], off
	v_lshl_add_u64 v[218:219], v[218:219], 0, s[6:7]
	v_mfma_f32_32x32x16_bf16 v[48:63], v[192:195], v[156:159], v[48:63]
	v_mfma_f32_32x32x16_bf16 v[32:47], v[208:211], v[156:159], v[32:47]
	v_mfma_f32_32x32x16_bf16 v[16:31], v[192:195], v[180:183], v[16:31]
	v_mfma_f32_32x32x16_bf16 v[0:15], v[208:211], v[180:183], v[0:15]
	s_add_u32 m0, s29, 0x24000
	s_nop 0
	global_load_lds_dwordx4 v[222:223], off
	v_lshl_add_u64 v[222:223], v[222:223], 0, s[6:7]
	s_sub_u32 s30, s30, 1
	s_cmp_lg_u32 s30, 0
	s_cbranch_scc1 .Lgk_ph7_loop
; #define G_LOADA(kt_) { _Pragma("unroll") for (int i = 0; i < 4; ++i) ra[i] = al(lrow + 64 * i, (kt_) * 64 + lck * 8); }
; #define G_LOADB(kt_) { _Pragma("unroll") for (int i = 0; i < 4; ++i) rb[i] = bl(lrow + 64 * i, (kt_) * 64 + lck * 8); }
; #define G_STOREA(buf_) { bf16_t* nA = sA + (buf_) * 256 * GLD; _Pragma("unroll") for (int i = 0; i < 4; ++i) *(u32x4*)(nA + (lrow + 64 * i) * GLD + lck * 8) = ra[i]; }
; #define G_STOREB(buf_) { bf16_t* nB = sB + (buf_) * 256 * GLD; _Pragma("unroll") for (int i = 0; i < 4; ++i) *(u32x4*)(nB + (lrow + 64 * i) * GLD + lck * 8) = rb[i]; }
; template <class AL, class BL, class EP>
; DI void gemm_tile256(AL al, BL bl, EP ep, int K, char* smem) {
;     ...
;   G_LOADA(0); G_LOADB(0);
;   __syncthreads();
;   G_STOREA(0); G_STOREB(0);
;   if (KT > 1) G_LOADB(1);
;   __syncthreads();
;   for (int kt = 0; kt < KT; kt += 2) {
;     G_STEP(0, kt);
;     if (kt + 1 >= KT) break;
;     G_STEP(1, kt + 1);
;   }
	s_waitcnt lgkmcnt(0)
	v_mfma_f32_32x32x16_bf16 v[112:127], v[184:187], v[132:135], v[112:127]
	ds_read_b128 v[192:195], v205
	ds_read_b128 v[148:151], v130
	v_mfma_f32_32x32x16_bf16 v[96:111], v[188:191], v[132:135], v[96:111]
	ds_read_b128 v[208:211], v205 offset:2048
	ds_read_b128 v[152:155], v130 offset:2048
	v_mfma_f32_32x32x16_bf16 v[80:95], v[184:187], v[136:139], v[80:95]
	ds_read_b128 v[156:159], v130 offset:4096
	ds_read_b128 v[180:183], v130 offset:6144
	v_mfma_f32_32x32x16_bf16 v[64:79], v[188:191], v[136:139], v[64:79]
	s_add_u32 m0, s29, 0x22000
	s_nop 0
	global_load_lds_dwordx4 v[220:221], off
	v_lshl_add_u64 v[220:221], v[220:221], 0, s[6:7]
	v_mfma_f32_32x32x16_bf16 v[48:63], v[184:187], v[140:143], v[48:63]
	v_mfma_f32_32x32x16_bf16 v[32:47], v[188:191], v[140:143], v[32:47]
	v_mfma_f32_32x32x16_bf16 v[16:31], v[184:187], v[144:147], v[16:31]
	v_mfma_f32_32x32x16_bf16 v[0:15], v[188:191], v[144:147], v[0:15]
	s_add_u32 m0, s29, 0x26000
	s_nop 0
	global_load_lds_dwordx4 v[224:225], off
	v_lshl_add_u64 v[224:225], v[224:225], 0, s[6:7]
	s_waitcnt lgkmcnt(0)
	s_waitcnt vmcnt(12)
	s_barrier
	s_waitcnt lgkmcnt(0)
	v_mfma_f32_32x32x16_bf16 v[112:127], v[192:195], v[148:151], v[112:127]
	ds_read_b128 v[184:187], v131 offset:32768
	ds_read_b128 v[132:135], v128 offset:32768
	v_mfma_f32_32x32x16_bf16 v[96:111], v[208:211], v[148:151], v[96:111]
	ds_read_b128 v[188:191], v131 offset:34816
	ds_read_b128 v[136:139], v128 offset:34816
	v_mfma_f32_32x32x16_bf16 v[80:95], v[192:195], v[152:155], v[80:95]
	ds_read_b128 v[140:143], v128 offset:36864
	ds_read_b128 v[144:147], v128 offset:38912
	v_mfma_f32_32x32x16_bf16 v[64:79], v[208:211], v[152:155], v[64:79]
	s_add_u32 m0, s29, 0x0
	s_nop 0
	global_load_lds_dwordx4 v[218:219], off
	v_lshl_add_u64 v[218:219], v[218:219], 0, s[6:7]
	v_mfma_f32_32x32x16_bf16 v[48:63], v[192:195], v[156:159], v[48:63]
	v_mfma_f32_32x32x16_bf16 v[32:47], v[208:211], v[156:159], v[32:47]
	v_mfma_f32_32x32x16_bf16 v[16:31], v[192:195], v[180:183], v[16:31]
	v_mfma_f32_32x32x16_bf16 v[0:15], v[208:211], v[180:183], v[0:15]
	s_add_u32 m0, s29, 0x4000
	s_nop 0
	global_load_lds_dwordx4 v[222:223], off
	v_lshl_add_u64 v[222:223], v[222:223], 0, s[6:7]
	s_waitcnt lgkmcnt(0)
	v_mfma_f32_32x32x16_bf16 v[112:127], v[184:187], v[132:135], v[112:127]
	ds_read_b128 v[192:195], v205 offset:32768
	ds_read_b128 v[148:151], v130 offset:32768
	v_mfma_f32_32x32x16_bf16 v[96:111], v[188:191], v[132:135], v[96:111]
	ds_read_b128 v[208:211], v205 offset:34816
	ds_read_b128 v[152:155], v130 offset:34816
	v_mfma_f32_32x32x16_bf16 v[80:95], v[184:187], v[136:139], v[80:95]
	ds_read_b128 v[156:159], v130 offset:36864
	ds_read_b128 v[180:183], v130 offset:38912
	v_mfma_f32_32x32x16_bf16 v[64:79], v[188:191], v[136:139], v[64:79]
	s_add_u32 m0, s29, 0x2000
	s_nop 0
	global_load_lds_dwordx4 v[220:221], off
	v_lshl_add_u64 v[220:221], v[220:221], 0, s[6:7]
	v_mfma_f32_32x32x16_bf16 v[48:63], v[184:187], v[140:143], v[48:63]
	v_mfma_f32_32x32x16_bf16 v[32:47], v[188:191], v[140:143], v[32:47]
	v_mfma_f32_32x32x16_bf16 v[16:31], v[184:187], v[144:147], v[16:31]
	v_mfma_f32_32x32x16_bf16 v[0:15], v[188:191], v[144:147], v[0:15]
	s_add_u32 m0, s29, 0x6000
	s_nop 0
	global_load_lds_dwordx4 v[224:225], off
	v_lshl_add_u64 v[224:225], v[224:225], 0, s[6:7]
	s_waitcnt lgkmcnt(0)
	s_waitcnt vmcnt(12)
	s_barrier
	s_waitcnt lgkmcnt(0)
	v_mfma_f32_32x32x16_bf16 v[112:127], v[192:195], v[148:151], v[112:127]
	ds_read_b128 v[184:187], v212
	ds_read_b128 v[132:135], v206
	v_mfma_f32_32x32x16_bf16 v[96:111], v[208:211], v[148:151], v[96:111]
	ds_read_b128 v[188:191], v212 offset:2048
	ds_read_b128 v[136:139], v206 offset:2048
	v_mfma_f32_32x32x16_bf16 v[80:95], v[192:195], v[152:155], v[80:95]
	ds_read_b128 v[140:143], v206 offset:4096
	ds_read_b128 v[144:147], v206 offset:6144
	v_mfma_f32_32x32x16_bf16 v[64:79], v[208:211], v[152:155], v[64:79]
	s_add_u32 m0, s29, 0x8000
	s_nop 0
	global_load_lds_dwordx4 v[218:219], off
	v_lshl_add_u64 v[218:219], v[218:219], 0, s[6:7]
	v_mfma_f32_32x32x16_bf16 v[48:63], v[192:195], v[156:159], v[48:63]
	v_mfma_f32_32x32x16_bf16 v[32:47], v[208:211], v[156:159], v[32:47]
	v_mfma_f32_32x32x16_bf16 v[16:31], v[192:195], v[180:183], v[16:31]
	v_mfma_f32_32x32x16_bf16 v[0:15], v[208:211], v[180:183], v[0:15]
	s_add_u32 m0, s29, 0xc000
	s_nop 0
	global_load_lds_dwordx4 v[222:223], off
	v_lshl_add_u64 v[222:223], v[222:223], 0, s[6:7]
	s_waitcnt lgkmcnt(0)
	v_mfma_f32_32x32x16_bf16 v[112:127], v[184:187], v[132:135], v[112:127]
	ds_read_b128 v[192:195], v213
	ds_read_b128 v[148:151], v207
	v_mfma_f32_32x32x16_bf16 v[96:111], v[188:191], v[132:135], v[96:111]
	ds_read_b128 v[208:211], v213 offset:2048
	ds_read_b128 v[152:155], v207 offset:2048
	v_mfma_f32_32x32x16_bf16 v[80:95], v[184:187], v[136:139], v[80:95]
	ds_read_b128 v[156:159], v207 offset:4096
	ds_read_b128 v[180:183], v207 offset:6144
	v_mfma_f32_32x32x16_bf16 v[64:79], v[188:191], v[136:139], v[64:79]
	s_add_u32 m0, s29, 0xa000
	s_nop 0
	global_load_lds_dwordx4 v[220:221], off
	v_lshl_add_u64 v[220:221], v[220:221], 0, s[6:7]
	v_mfma_f32_32x32x16_bf16 v[48:63], v[184:187], v[140:143], v[48:63]
	v_mfma_f32_32x32x16_bf16 v[32:47], v[188:191], v[140:143], v[32:47]
	v_mfma_f32_32x32x16_bf16 v[16:31], v[184:187], v[144:147], v[16:31]
	v_mfma_f32_32x32x16_bf16 v[0:15], v[188:191], v[144:147], v[0:15]
	s_add_u32 m0, s29, 0xe000
	s_nop 0
	global_load_lds_dwordx4 v[224:225], off
	v_lshl_add_u64 v[224:225], v[224:225], 0, s[6:7]
	s_waitcnt lgkmcnt(0)
	s_waitcnt vmcnt(12)
	s_barrier
; #define G_LOADA(kt_) { _Pragma("unroll") for (int i = 0; i < 4; ++i) ra[i] = al(lrow + 64 * i, (kt_) * 64 + lck * 8); }
; #define G_LOADB(kt_) { _Pragma("unroll") for (int i = 0; i < 4; ++i) rb[i] = bl(lrow + 64 * i, (kt_) * 64 + lck * 8); }
; #define G_STOREA(buf_) { bf16_t* nA = sA + (buf_) * 256 * GLD; _Pragma("unroll") for (int i = 0; i < 4; ++i) *(u32x4*)(nA + (lrow + 64 * i) * GLD + lck * 8) = ra[i]; }
; #define G_STOREB(buf_) { bf16_t* nB = sB + (buf_) * 256 * GLD; _Pragma("unroll") for (int i = 0; i < 4; ++i) *(u32x4*)(nB + (lrow + 64 * i) * GLD + lck * 8) = rb[i]; }
; template <class AL, class BL, class EP>
; DI void gemm_tile256(AL al, BL bl, EP ep, int K, char* smem) {
;     ...
;   G_LOADA(0); G_LOADB(0);
;   __syncthreads();
;   G_STOREA(0); G_STOREB(0);
;   if (KT > 1) G_LOADB(1);
;   __syncthreads();
;   for (int kt = 0; kt < KT; kt += 2) {
;     G_STEP(0, kt);
;     if (kt + 1 >= KT) break;
;     G_STEP(1, kt + 1);
;   }
	s_waitcnt lgkmcnt(0)
	v_mfma_f32_32x32x16_bf16 v[112:127], v[192:195], v[148:151], v[112:127]
	ds_read_b128 v[184:187], v212 offset:32768
	ds_read_b128 v[132:135], v206 offset:32768
	v_mfma_f32_32x32x16_bf16 v[96:111], v[208:211], v[148:151], v[96:111]
	ds_read_b128 v[188:191], v212 offset:34816
	ds_read_b128 v[136:139], v206 offset:34816
	v_mfma_f32_32x32x16_bf16 v[80:95], v[192:195], v[152:155], v[80:95]
	ds_read_b128 v[140:143], v206 offset:36864
	ds_read_b128 v[144:147], v206 offset:38912
	v_mfma_f32_32x32x16_bf16 v[64:79], v[208:211], v[152:155], v[64:79]
	s_add_u32 m0, s29, 0x10000
	s_nop 0
	global_load_lds_dwordx4 v[218:219], off
	v_lshl_add_u64 v[218:219], v[218:219], 0, s[6:7]
	v_mfma_f32_32x32x16_bf16 v[48:63], v[192:195], v[156:159], v[48:63]
	v_mfma_f32_32x32x16_bf16 v[32:47], v[208:211], v[156:159], v[32:47]
	v_mfma_f32_32x32x16_bf16 v[16:31], v[192:195], v[180:183], v[16:31]
	v_mfma_f32_32x32x16_bf16 v[0:15], v[208:211], v[180:183], v[0:15]
	s_add_u32 m0, s29, 0x14000
	s_nop 0
	global_load_lds_dwordx4 v[222:223], off
	v_lshl_add_u64 v[222:223], v[222:223], 0, s[6:7]
	s_waitcnt lgkmcnt(0)
	v_mfma_f32_32x32x16_bf16 v[112:127], v[184:187], v[132:135], v[112:127]
	ds_read_b128 v[192:195], v213 offset:32768
	ds_read_b128 v[148:151], v207 offset:32768
	v_mfma_f32_32x32x16_bf16 v[96:111], v[188:191], v[132:135], v[96:111]
	ds_read_b128 v[208:211], v213 offset:34816
	ds_read_b128 v[152:155], v207 offset:34816
	v_mfma_f32_32x32x16_bf16 v[80:95], v[184:187], v[136:139], v[80:95]
	ds_read_b128 v[156:159], v207 offset:36864
	ds_read_b128 v[180:183], v207 offset:38912
	v_mfma_f32_32x32x16_bf16 v[64:79], v[188:191], v[136:139], v[64:79]
	s_add_u32 m0, s29, 0x12000
	s_nop 0
	global_load_lds_dwordx4 v[220:221], off
	v_lshl_add_u64 v[220:221], v[220:221], 0, s[6:7]
	v_mfma_f32_32x32x16_bf16 v[48:63], v[184:187], v[140:143], v[48:63]
	v_mfma_f32_32x32x16_bf16 v[32:47], v[188:191], v[140:143], v[32:47]
	v_mfma_f32_32x32x16_bf16 v[16:31], v[184:187], v[144:147], v[16:31]
	v_mfma_f32_32x32x16_bf16 v[0:15], v[188:191], v[144:147], v[0:15]
	s_add_u32 m0, s29, 0x16000
	s_nop 0
	global_load_lds_dwordx4 v[224:225], off
	v_lshl_add_u64 v[224:225], v[224:225], 0, s[6:7]
	s_waitcnt lgkmcnt(0)
	s_waitcnt vmcnt(12)
	s_barrier
	s_waitcnt lgkmcnt(0)
	v_mfma_f32_32x32x16_bf16 v[112:127], v[192:195], v[148:151], v[112:127]
	ds_read_b128 v[184:187], v216
	ds_read_b128 v[132:135], v214
	v_mfma_f32_32x32x16_bf16 v[96:111], v[208:211], v[148:151], v[96:111]
	ds_read_b128 v[188:191], v216 offset:2048
	ds_read_b128 v[136:139], v214 offset:2048
	v_mfma_f32_32x32x16_bf16 v[80:95], v[192:195], v[152:155], v[80:95]
	ds_read_b128 v[140:143], v214 offset:4096
	ds_read_b128 v[144:147], v214 offset:6144
	v_mfma_f32_32x32x16_bf16 v[64:79], v[208:211], v[152:155], v[64:79]
	v_mfma_f32_32x32x16_bf16 v[48:63], v[192:195], v[156:159], v[48:63]
	v_mfma_f32_32x32x16_bf16 v[32:47], v[208:211], v[156:159], v[32:47]
	v_mfma_f32_32x32x16_bf16 v[16:31], v[192:195], v[180:183], v[16:31]
	v_mfma_f32_32x32x16_bf16 v[0:15], v[208:211], v[180:183], v[0:15]
	s_waitcnt lgkmcnt(0)
	v_mfma_f32_32x32x16_bf16 v[112:127], v[184:187], v[132:135], v[112:127]
	ds_read_b128 v[192:195], v217
	ds_read_b128 v[148:151], v215
	v_mfma_f32_32x32x16_bf16 v[96:111], v[188:191], v[132:135], v[96:111]
	ds_read_b128 v[208:211], v217 offset:2048
	ds_read_b128 v[152:155], v215 offset:2048
	v_mfma_f32_32x32x16_bf16 v[80:95], v[184:187], v[136:139], v[80:95]
	ds_read_b128 v[156:159], v215 offset:4096
	ds_read_b128 v[180:183], v215 offset:6144
	v_mfma_f32_32x32x16_bf16 v[64:79], v[188:191], v[136:139], v[64:79]
	v_mfma_f32_32x32x16_bf16 v[48:63], v[184:187], v[140:143], v[48:63]
	v_mfma_f32_32x32x16_bf16 v[32:47], v[188:191], v[140:143], v[32:47]
	v_mfma_f32_32x32x16_bf16 v[16:31], v[184:187], v[144:147], v[16:31]
	v_mfma_f32_32x32x16_bf16 v[0:15], v[188:191], v[144:147], v[0:15]
	s_waitcnt lgkmcnt(0)
	s_waitcnt vmcnt(8)
	s_barrier
	s_waitcnt lgkmcnt(0)
	v_mfma_f32_32x32x16_bf16 v[112:127], v[192:195], v[148:151], v[112:127]
	ds_read_b128 v[184:187], v131
	ds_read_b128 v[132:135], v128
	v_mfma_f32_32x32x16_bf16 v[96:111], v[208:211], v[148:151], v[96:111]
	ds_read_b128 v[188:191], v131 offset:2048
	ds_read_b128 v[136:139], v128 offset:2048
	v_mfma_f32_32x32x16_bf16 v[80:95], v[192:195], v[152:155], v[80:95]
	ds_read_b128 v[140:143], v128 offset:4096
	ds_read_b128 v[144:147], v128 offset:6144
	v_mfma_f32_32x32x16_bf16 v[64:79], v[208:211], v[152:155], v[64:79]
	v_mfma_f32_32x32x16_bf16 v[48:63], v[192:195], v[156:159], v[48:63]
	v_mfma_f32_32x32x16_bf16 v[32:47], v[208:211], v[156:159], v[32:47]
	v_mfma_f32_32x32x16_bf16 v[16:31], v[192:195], v[180:183], v[16:31]
	v_mfma_f32_32x32x16_bf16 v[0:15], v[208:211], v[180:183], v[0:15]
	s_waitcnt lgkmcnt(0)
	v_mfma_f32_32x32x16_bf16 v[112:127], v[184:187], v[132:135], v[112:127]
	ds_read_b128 v[192:195], v205
	ds_read_b128 v[148:151], v130
	v_mfma_f32_32x32x16_bf16 v[96:111], v[188:191], v[132:135], v[96:111]
	ds_read_b128 v[208:211], v205 offset:2048
	ds_read_b128 v[152:155], v130 offset:2048
	v_mfma_f32_32x32x16_bf16 v[80:95], v[184:187], v[136:139], v[80:95]
	ds_read_b128 v[156:159], v130 offset:4096
	ds_read_b128 v[180:183], v130 offset:6144
	v_mfma_f32_32x32x16_bf16 v[64:79], v[188:191], v[136:139], v[64:79]
	v_mfma_f32_32x32x16_bf16 v[48:63], v[184:187], v[140:143], v[48:63]
	v_mfma_f32_32x32x16_bf16 v[32:47], v[188:191], v[140:143], v[32:47]
	v_mfma_f32_32x32x16_bf16 v[16:31], v[184:187], v[144:147], v[16:31]
	v_mfma_f32_32x32x16_bf16 v[0:15], v[188:191], v[144:147], v[0:15]
	s_waitcnt lgkmcnt(0)
	s_waitcnt vmcnt(4)
	s_barrier
; #define G_LOADA(kt_) { _Pragma("unroll") for (int i = 0; i < 4; ++i) ra[i] = al(lrow + 64 * i, (kt_) * 64 + lck * 8); }
; #define G_LOADB(kt_) { _Pragma("unroll") for (int i = 0; i < 4; ++i) rb[i] = bl(lrow + 64 * i, (kt_) * 64 + lck * 8); }
; #define G_STOREA(buf_) { bf16_t* nA = sA + (buf_) * 256 * GLD; _Pragma("unroll") for (int i = 0; i < 4; ++i) *(u32x4*)(nA + (lrow + 64 * i) * GLD + lck * 8) = ra[i]; }
; #define G_STOREB(buf_) { bf16_t* nB = sB + (buf_) * 256 * GLD; _Pragma("unroll") for (int i = 0; i < 4; ++i) *(u32x4*)(nB + (lrow + 64 * i) * GLD + lck * 8) = rb[i]; }
; template <class AL, class BL, class EP>
; DI void gemm_tile256(AL al, BL bl, EP ep, int K, char* smem) {
;     ...
;   G_LOADA(0); G_LOADB(0);
;   __syncthreads();
;   G_STOREA(0); G_STOREB(0);
;   if (KT > 1) G_LOADB(1);
;   __syncthreads();
;   for (int kt = 0; kt < KT; kt += 2) {
;     G_STEP(0, kt);
;     if (kt + 1 >= KT) break;
;     G_STEP(1, kt + 1);
;   }
;     ...
;     __syncthreads();
	s_waitcnt lgkmcnt(0)
	v_mfma_f32_32x32x16_bf16 v[112:127], v[192:195], v[148:151], v[112:127]
	ds_read_b128 v[184:187], v131 offset:32768
	ds_read_b128 v[132:135], v128 offset:32768
	v_mfma_f32_32x32x16_bf16 v[96:111], v[208:211], v[148:151], v[96:111]
	ds_read_b128 v[188:191], v131 offset:34816
	ds_read_b128 v[136:139], v128 offset:34816
	v_mfma_f32_32x32x16_bf16 v[80:95], v[192:195], v[152:155], v[80:95]
	ds_read_b128 v[140:143], v128 offset:36864
	ds_read_b128 v[144:147], v128 offset:38912
	v_mfma_f32_32x32x16_bf16 v[64:79], v[208:211], v[152:155], v[64:79]
	v_mfma_f32_32x32x16_bf16 v[48:63], v[192:195], v[156:159], v[48:63]
	v_mfma_f32_32x32x16_bf16 v[32:47], v[208:211], v[156:159], v[32:47]
	v_mfma_f32_32x32x16_bf16 v[16:31], v[192:195], v[180:183], v[16:31]
	v_mfma_f32_32x32x16_bf16 v[0:15], v[208:211], v[180:183], v[0:15]
	s_waitcnt lgkmcnt(0)
	v_mfma_f32_32x32x16_bf16 v[112:127], v[184:187], v[132:135], v[112:127]
	ds_read_b128 v[192:195], v205 offset:32768
	ds_read_b128 v[148:151], v130 offset:32768
	v_mfma_f32_32x32x16_bf16 v[96:111], v[188:191], v[132:135], v[96:111]
	ds_read_b128 v[208:211], v205 offset:34816
	ds_read_b128 v[152:155], v130 offset:34816
	v_mfma_f32_32x32x16_bf16 v[80:95], v[184:187], v[136:139], v[80:95]
	ds_read_b128 v[156:159], v130 offset:36864
	ds_read_b128 v[180:183], v130 offset:38912
	v_mfma_f32_32x32x16_bf16 v[64:79], v[188:191], v[136:139], v[64:79]
	v_mfma_f32_32x32x16_bf16 v[48:63], v[184:187], v[140:143], v[48:63]
	v_mfma_f32_32x32x16_bf16 v[32:47], v[188:191], v[140:143], v[32:47]
	v_mfma_f32_32x32x16_bf16 v[16:31], v[184:187], v[144:147], v[16:31]
	v_mfma_f32_32x32x16_bf16 v[0:15], v[188:191], v[144:147], v[0:15]
	s_waitcnt lgkmcnt(0)
	s_waitcnt vmcnt(0)
	s_barrier
	s_waitcnt lgkmcnt(0)
	v_mfma_f32_32x32x16_bf16 v[112:127], v[192:195], v[148:151], v[112:127]
	ds_read_b128 v[184:187], v212
	ds_read_b128 v[132:135], v206
	v_mfma_f32_32x32x16_bf16 v[96:111], v[208:211], v[148:151], v[96:111]
	ds_read_b128 v[188:191], v212 offset:2048
	ds_read_b128 v[136:139], v206 offset:2048
	v_mfma_f32_32x32x16_bf16 v[80:95], v[192:195], v[152:155], v[80:95]
	ds_read_b128 v[140:143], v206 offset:4096
	ds_read_b128 v[144:147], v206 offset:6144
	v_mfma_f32_32x32x16_bf16 v[64:79], v[208:211], v[152:155], v[64:79]
	v_mfma_f32_32x32x16_bf16 v[48:63], v[192:195], v[156:159], v[48:63]
	v_mfma_f32_32x32x16_bf16 v[32:47], v[208:211], v[156:159], v[32:47]
	v_mfma_f32_32x32x16_bf16 v[16:31], v[192:195], v[180:183], v[16:31]
	v_mfma_f32_32x32x16_bf16 v[0:15], v[208:211], v[180:183], v[0:15]
	s_waitcnt lgkmcnt(0)
	v_mfma_f32_32x32x16_bf16 v[112:127], v[184:187], v[132:135], v[112:127]
	ds_read_b128 v[192:195], v213
	ds_read_b128 v[148:151], v207
	v_mfma_f32_32x32x16_bf16 v[96:111], v[188:191], v[132:135], v[96:111]
	ds_read_b128 v[208:211], v213 offset:2048
	ds_read_b128 v[152:155], v207 offset:2048
	v_mfma_f32_32x32x16_bf16 v[80:95], v[184:187], v[136:139], v[80:95]
	ds_read_b128 v[156:159], v207 offset:4096
	ds_read_b128 v[180:183], v207 offset:6144
	v_mfma_f32_32x32x16_bf16 v[64:79], v[188:191], v[136:139], v[64:79]
	v_mfma_f32_32x32x16_bf16 v[48:63], v[184:187], v[140:143], v[48:63]
	v_mfma_f32_32x32x16_bf16 v[32:47], v[188:191], v[140:143], v[32:47]
	v_mfma_f32_32x32x16_bf16 v[16:31], v[184:187], v[144:147], v[16:31]
	v_mfma_f32_32x32x16_bf16 v[0:15], v[188:191], v[144:147], v[0:15]
	s_waitcnt lgkmcnt(0)
	s_waitcnt lgkmcnt(0)
	v_mfma_f32_32x32x16_bf16 v[112:127], v[192:195], v[148:151], v[112:127]
	v_mfma_f32_32x32x16_bf16 v[96:111], v[208:211], v[148:151], v[96:111]
	v_mfma_f32_32x32x16_bf16 v[80:95], v[192:195], v[152:155], v[80:95]
	v_mfma_f32_32x32x16_bf16 v[64:79], v[208:211], v[152:155], v[64:79]
	v_mfma_f32_32x32x16_bf16 v[48:63], v[192:195], v[156:159], v[48:63]
	v_mfma_f32_32x32x16_bf16 v[32:47], v[208:211], v[156:159], v[32:47]
	v_mfma_f32_32x32x16_bf16 v[16:31], v[192:195], v[180:183], v[16:31]
	v_mfma_f32_32x32x16_bf16 v[0:15], v[208:211], v[180:183], v[0:15]
	s_nop 15
	s_nop 3
	s_barrier
	s_branch .LBB0_666

; #define G_LOADA(kt_) { _Pragma("unroll") for (int i = 0; i < 4; ++i) ra[i] = al(lrow + 64 * i, (kt_) * 64 + lck * 8); }
; #define G_LOADB(kt_) { _Pragma("unroll") for (int i = 0; i < 4; ++i) rb[i] = bl(lrow + 64 * i, (kt_) * 64 + lck * 8); }
; #define G_STOREA(buf_) { bf16_t* nA = sA + (buf_) * 256 * GLD; _Pragma("unroll") for (int i = 0; i < 4; ++i) *(u32x4*)(nA + (lrow + 64 * i) * GLD + lck * 8) = ra[i]; }
; #define G_STOREB(buf_) { bf16_t* nB = sB + (buf_) * 256 * GLD; _Pragma("unroll") for (int i = 0; i < 4; ++i) *(u32x4*)(nB + (lrow + 64 * i) * GLD + lck * 8) = rb[i]; }
; template <class AL, class BL, class EP>
; DI void gemm_tile256(AL al, BL bl, EP ep, int K, char* smem) {
;     ...
;   G_LOADA(0); G_LOADB(0);
;   __syncthreads();
;   G_STOREA(0); G_STOREB(0);
;   if (KT > 1) G_LOADB(1);
;   __syncthreads();
;   for (int kt = 0; kt < KT; kt += 2) {
;     G_STEP(0, kt);
;     if (kt + 1 >= KT) break;
;     G_STEP(1, kt + 1);
;   }
.Lgk_ph16_loop:
	s_waitcnt lgkmcnt(0)
	v_mfma_f32_32x32x16_bf16 v[112:127], v[184:187], v[132:135], v[112:127]
	ds_read_b128 v[192:195], v205
	ds_read_b128 v[148:151], v130
	v_mfma_f32_32x32x16_bf16 v[96:111], v[188:191], v[132:135], v[96:111]
	ds_read_b128 v[208:211], v205 offset:2048
	ds_read_b128 v[152:155], v130 offset:2048
	v_mfma_f32_32x32x16_bf16 v[80:95], v[184:187], v[136:139], v[80:95]
	ds_read_b128 v[156:159], v130 offset:4096
	ds_read_b128 v[180:183], v130 offset:6144
	v_mfma_f32_32x32x16_bf16 v[64:79], v[188:191], v[136:139], v[64:79]
	s_add_u32 m0, s26, 0x22000
	s_nop 0
	global_load_lds_dwordx4 v[220:221], off
	v_lshl_add_u64 v[220:221], v[220:221], 0, s[6:7]
	v_mfma_f32_32x32x16_bf16 v[48:63], v[184:187], v[140:143], v[48:63]
	v_mfma_f32_32x32x16_bf16 v[32:47], v[188:191], v[140:143], v[32:47]
	v_mfma_f32_32x32x16_bf16 v[16:31], v[184:187], v[144:147], v[16:31]
	v_mfma_f32_32x32x16_bf16 v[0:15], v[188:191], v[144:147], v[0:15]
	s_add_u32 m0, s26, 0x26000
	s_nop 0
	global_load_lds_dwordx4 v[224:225], off
	v_lshl_add_u64 v[224:225], v[224:225], 0, s[6:7]
	s_waitcnt lgkmcnt(0)
	s_waitcnt vmcnt(12)
	s_barrier
	s_waitcnt lgkmcnt(0)
	v_mfma_f32_32x32x16_bf16 v[112:127], v[192:195], v[148:151], v[112:127]
	ds_read_b128 v[184:187], v131 offset:32768
	ds_read_b128 v[132:135], v128 offset:32768
	v_mfma_f32_32x32x16_bf16 v[96:111], v[208:211], v[148:151], v[96:111]
	ds_read_b128 v[188:191], v131 offset:34816
	ds_read_b128 v[136:139], v128 offset:34816
	v_mfma_f32_32x32x16_bf16 v[80:95], v[192:195], v[152:155], v[80:95]
	ds_read_b128 v[140:143], v128 offset:36864
	ds_read_b128 v[144:147], v128 offset:38912
	v_mfma_f32_32x32x16_bf16 v[64:79], v[208:211], v[152:155], v[64:79]
	s_add_u32 m0, s26, 0x0
	s_nop 0
	global_load_lds_dwordx4 v[218:219], off
	v_lshl_add_u64 v[218:219], v[218:219], 0, s[6:7]
	v_mfma_f32_32x32x16_bf16 v[48:63], v[192:195], v[156:159], v[48:63]
	v_mfma_f32_32x32x16_bf16 v[32:47], v[208:211], v[156:159], v[32:47]
	v_mfma_f32_32x32x16_bf16 v[16:31], v[192:195], v[180:183], v[16:31]
	v_mfma_f32_32x32x16_bf16 v[0:15], v[208:211], v[180:183], v[0:15]
	s_add_u32 m0, s26, 0x4000
	s_nop 0
	global_load_lds_dwordx4 v[222:223], off
	v_lshl_add_u64 v[222:223], v[222:223], 0, s[6:7]
	s_waitcnt lgkmcnt(0)
	v_mfma_f32_32x32x16_bf16 v[112:127], v[184:187], v[132:135], v[112:127]
	ds_read_b128 v[192:195], v205 offset:32768
	ds_read_b128 v[148:151], v130 offset:32768
	v_mfma_f32_32x32x16_bf16 v[96:111], v[188:191], v[132:135], v[96:111]
	ds_read_b128 v[208:211], v205 offset:34816
	ds_read_b128 v[152:155], v130 offset:34816
	v_mfma_f32_32x32x16_bf16 v[80:95], v[184:187], v[136:139], v[80:95]
	ds_read_b128 v[156:159], v130 offset:36864
	ds_read_b128 v[180:183], v130 offset:38912
	v_mfma_f32_32x32x16_bf16 v[64:79], v[188:191], v[136:139], v[64:79]
	s_add_u32 m0, s26, 0x2000
	s_nop 0
	global_load_lds_dwordx4 v[220:221], off
	v_lshl_add_u64 v[220:221], v[220:221], 0, s[6:7]
	v_mfma_f32_32x32x16_bf16 v[48:63], v[184:187], v[140:143], v[48:63]
	v_mfma_f32_32x32x16_bf16 v[32:47], v[188:191], v[140:143], v[32:47]
	v_mfma_f32_32x32x16_bf16 v[16:31], v[184:187], v[144:147], v[16:31]
	v_mfma_f32_32x32x16_bf16 v[0:15], v[188:191], v[144:147], v[0:15]
	s_add_u32 m0, s26, 0x6000
	s_nop 0
	global_load_lds_dwordx4 v[224:225], off
	v_lshl_add_u64 v[224:225], v[224:225], 0, s[6:7]
	s_waitcnt lgkmcnt(0)
	s_waitcnt vmcnt(12)
	s_barrier
	s_waitcnt lgkmcnt(0)
	v_mfma_f32_32x32x16_bf16 v[112:127], v[192:195], v[148:151], v[112:127]
	ds_read_b128 v[184:187], v212
	ds_read_b128 v[132:135], v206
	v_mfma_f32_32x32x16_bf16 v[96:111], v[208:211], v[148:151], v[96:111]
	ds_read_b128 v[188:191], v212 offset:2048
	ds_read_b128 v[136:139], v206 offset:2048
	v_mfma_f32_32x32x16_bf16 v[80:95], v[192:195], v[152:155], v[80:95]
	ds_read_b128 v[140:143], v206 offset:4096
	ds_read_b128 v[144:147], v206 offset:6144
	v_mfma_f32_32x32x16_bf16 v[64:79], v[208:211], v[152:155], v[64:79]
	s_add_u32 m0, s26, 0x8000
	s_nop 0
	global_load_lds_dwordx4 v[218:219], off
	v_lshl_add_u64 v[218:219], v[218:219], 0, s[6:7]
	v_mfma_f32_32x32x16_bf16 v[48:63], v[192:195], v[156:159], v[48:63]
	v_mfma_f32_32x32x16_bf16 v[32:47], v[208:211], v[156:159], v[32:47]
	v_mfma_f32_32x32x16_bf16 v[16:31], v[192:195], v[180:183], v[16:31]
	v_mfma_f32_32x32x16_bf16 v[0:15], v[208:211], v[180:183], v[0:15]
	s_add_u32 m0, s26, 0xc000
	s_nop 0
	global_load_lds_dwordx4 v[222:223], off
	v_lshl_add_u64 v[222:223], v[222:223], 0, s[6:7]
	s_waitcnt lgkmcnt(0)
	v_mfma_f32_32x32x16_bf16 v[112:127], v[184:187], v[132:135], v[112:127]
	ds_read_b128 v[192:195], v213
	ds_read_b128 v[148:151], v207
	v_mfma_f32_32x32x16_bf16 v[96:111], v[188:191], v[132:135], v[96:111]
	ds_read_b128 v[208:211], v213 offset:2048
	ds_read_b128 v[152:155], v207 offset:2048
	v_mfma_f32_32x32x16_bf16 v[80:95], v[184:187], v[136:139], v[80:95]
	ds_read_b128 v[156:159], v207 offset:4096
	ds_read_b128 v[180:183], v207 offset:6144
	v_mfma_f32_32x32x16_bf16 v[64:79], v[188:191], v[136:139], v[64:79]
	s_add_u32 m0, s26, 0xa000
	s_nop 0
	global_load_lds_dwordx4 v[220:221], off
	v_lshl_add_u64 v[220:221], v[220:221], 0, s[6:7]
	v_mfma_f32_32x32x16_bf16 v[48:63], v[184:187], v[140:143], v[48:63]
	v_mfma_f32_32x32x16_bf16 v[32:47], v[188:191], v[140:143], v[32:47]
	v_mfma_f32_32x32x16_bf16 v[16:31], v[184:187], v[144:147], v[16:31]
	v_mfma_f32_32x32x16_bf16 v[0:15], v[188:191], v[144:147], v[0:15]
	s_add_u32 m0, s26, 0xe000
	s_nop 0
	global_load_lds_dwordx4 v[224:225], off
	v_lshl_add_u64 v[224:225], v[224:225], 0, s[6:7]
	s_waitcnt lgkmcnt(0)
	s_waitcnt vmcnt(12)
	s_barrier
; #define G_LOADA(kt_) { _Pragma("unroll") for (int i = 0; i < 4; ++i) ra[i] = al(lrow + 64 * i, (kt_) * 64 + lck * 8); }
; #define G_LOADB(kt_) { _Pragma("unroll") for (int i = 0; i < 4; ++i) rb[i] = bl(lrow + 64 * i, (kt_) * 64 + lck * 8); }
; #define G_STOREA(buf_) { bf16_t* nA = sA + (buf_) * 256 * GLD; _Pragma("unroll") for (int i = 0; i < 4; ++i) *(u32x4*)(nA + (lrow + 64 * i) * GLD + lck * 8) = ra[i]; }
; #define G_STOREB(buf_) { bf16_t* nB = sB + (buf_) * 256 * GLD; _Pragma("unroll") for (int i = 0; i < 4; ++i) *(u32x4*)(nB + (lrow + 64 * i) * GLD + lck * 8) = rb[i]; }
; template <class AL, class BL, class EP>
; DI void gemm_tile256(AL al, BL bl, EP ep, int K, char* smem) {
;     ...
;   G_LOADA(0); G_LOADB(0);
;   __syncthreads();
;   G_STOREA(0); G_STOREB(0);
;   if (KT > 1) G_LOADB(1);
;   __syncthreads();
;   for (int kt = 0; kt < KT; kt += 2) {
;     G_STEP(0, kt);
;     if (kt + 1 >= KT) break;
;     G_STEP(1, kt + 1);
;   }
	s_waitcnt lgkmcnt(0)
	v_mfma_f32_32x32x16_bf16 v[112:127], v[192:195], v[148:151], v[112:127]
	ds_read_b128 v[184:187], v212 offset:32768
	ds_read_b128 v[132:135], v206 offset:32768
	v_mfma_f32_32x32x16_bf16 v[96:111], v[208:211], v[148:151], v[96:111]
	ds_read_b128 v[188:191], v212 offset:34816
	ds_read_b128 v[136:139], v206 offset:34816
	v_mfma_f32_32x32x16_bf16 v[80:95], v[192:195], v[152:155], v[80:95]
	ds_read_b128 v[140:143], v206 offset:36864
	ds_read_b128 v[144:147], v206 offset:38912
	v_mfma_f32_32x32x16_bf16 v[64:79], v[208:211], v[152:155], v[64:79]
	s_add_u32 m0, s26, 0x10000
	s_nop 0
	global_load_lds_dwordx4 v[218:219], off
	v_lshl_add_u64 v[218:219], v[218:219], 0, s[6:7]
	v_mfma_f32_32x32x16_bf16 v[48:63], v[192:195], v[156:159], v[48:63]
	v_mfma_f32_32x32x16_bf16 v[32:47], v[208:211], v[156:159], v[32:47]
	v_mfma_f32_32x32x16_bf16 v[16:31], v[192:195], v[180:183], v[16:31]
	v_mfma_f32_32x32x16_bf16 v[0:15], v[208:211], v[180:183], v[0:15]
	s_add_u32 m0, s26, 0x14000
	s_nop 0
	global_load_lds_dwordx4 v[222:223], off
	v_lshl_add_u64 v[222:223], v[222:223], 0, s[6:7]
	s_waitcnt lgkmcnt(0)
	v_mfma_f32_32x32x16_bf16 v[112:127], v[184:187], v[132:135], v[112:127]
	ds_read_b128 v[192:195], v213 offset:32768
	ds_read_b128 v[148:151], v207 offset:32768
	v_mfma_f32_32x32x16_bf16 v[96:111], v[188:191], v[132:135], v[96:111]
	ds_read_b128 v[208:211], v213 offset:34816
	ds_read_b128 v[152:155], v207 offset:34816
	v_mfma_f32_32x32x16_bf16 v[80:95], v[184:187], v[136:139], v[80:95]
	ds_read_b128 v[156:159], v207 offset:36864
	ds_read_b128 v[180:183], v207 offset:38912
	v_mfma_f32_32x32x16_bf16 v[64:79], v[188:191], v[136:139], v[64:79]
	s_add_u32 m0, s26, 0x12000
	s_nop 0
	global_load_lds_dwordx4 v[220:221], off
	v_lshl_add_u64 v[220:221], v[220:221], 0, s[6:7]
	v_mfma_f32_32x32x16_bf16 v[48:63], v[184:187], v[140:143], v[48:63]
	v_mfma_f32_32x32x16_bf16 v[32:47], v[188:191], v[140:143], v[32:47]
	v_mfma_f32_32x32x16_bf16 v[16:31], v[184:187], v[144:147], v[16:31]
	v_mfma_f32_32x32x16_bf16 v[0:15], v[188:191], v[144:147], v[0:15]
	s_add_u32 m0, s26, 0x16000
	s_nop 0
	global_load_lds_dwordx4 v[224:225], off
	v_lshl_add_u64 v[224:225], v[224:225], 0, s[6:7]
	s_waitcnt lgkmcnt(0)
	s_waitcnt vmcnt(12)
	s_barrier
	s_waitcnt lgkmcnt(0)
	v_mfma_f32_32x32x16_bf16 v[112:127], v[192:195], v[148:151], v[112:127]
	ds_read_b128 v[184:187], v216
	ds_read_b128 v[132:135], v214
	v_mfma_f32_32x32x16_bf16 v[96:111], v[208:211], v[148:151], v[96:111]
	ds_read_b128 v[188:191], v216 offset:2048
	ds_read_b128 v[136:139], v214 offset:2048
	v_mfma_f32_32x32x16_bf16 v[80:95], v[192:195], v[152:155], v[80:95]
	ds_read_b128 v[140:143], v214 offset:4096
	ds_read_b128 v[144:147], v214 offset:6144
	v_mfma_f32_32x32x16_bf16 v[64:79], v[208:211], v[152:155], v[64:79]
	s_add_u32 m0, s26, 0x18000
	s_nop 0
	global_load_lds_dwordx4 v[218:219], off
	v_lshl_add_u64 v[218:219], v[218:219], 0, s[6:7]
	v_mfma_f32_32x32x16_bf16 v[48:63], v[192:195], v[156:159], v[48:63]
	v_mfma_f32_32x32x16_bf16 v[32:47], v[208:211], v[156:159], v[32:47]
	v_mfma_f32_32x32x16_bf16 v[16:31], v[192:195], v[180:183], v[16:31]
	v_mfma_f32_32x32x16_bf16 v[0:15], v[208:211], v[180:183], v[0:15]
	s_add_u32 m0, s26, 0x1c000
	s_nop 0
	global_load_lds_dwordx4 v[222:223], off
	v_lshl_add_u64 v[222:223], v[222:223], 0, s[6:7]
	s_waitcnt lgkmcnt(0)
	v_mfma_f32_32x32x16_bf16 v[112:127], v[184:187], v[132:135], v[112:127]
	ds_read_b128 v[192:195], v217
	ds_read_b128 v[148:151], v215
	v_mfma_f32_32x32x16_bf16 v[96:111], v[188:191], v[132:135], v[96:111]
	ds_read_b128 v[208:211], v217 offset:2048
	ds_read_b128 v[152:155], v215 offset:2048
	v_mfma_f32_32x32x16_bf16 v[80:95], v[184:187], v[136:139], v[80:95]
	ds_read_b128 v[156:159], v215 offset:4096
	ds_read_b128 v[180:183], v215 offset:6144
	v_mfma_f32_32x32x16_bf16 v[64:79], v[188:191], v[136:139], v[64:79]
	s_add_u32 m0, s26, 0x1a000
	s_nop 0
	global_load_lds_dwordx4 v[220:221], off
	v_lshl_add_u64 v[220:221], v[220:221], 0, s[6:7]
	v_mfma_f32_32x32x16_bf16 v[48:63], v[184:187], v[140:143], v[48:63]
	v_mfma_f32_32x32x16_bf16 v[32:47], v[188:191], v[140:143], v[32:47]
	v_mfma_f32_32x32x16_bf16 v[16:31], v[184:187], v[144:147], v[16:31]
	v_mfma_f32_32x32x16_bf16 v[0:15], v[188:191], v[144:147], v[0:15]
	s_add_u32 m0, s26, 0x1e000
	s_nop 0
	global_load_lds_dwordx4 v[224:225], off
	v_lshl_add_u64 v[224:225], v[224:225], 0, s[6:7]
	s_waitcnt lgkmcnt(0)
	s_waitcnt vmcnt(12)
	s_barrier
	s_waitcnt lgkmcnt(0)
	v_mfma_f32_32x32x16_bf16 v[112:127], v[192:195], v[148:151], v[112:127]
	ds_read_b128 v[184:187], v131
	ds_read_b128 v[132:135], v128
	v_mfma_f32_32x32x16_bf16 v[96:111], v[208:211], v[148:151], v[96:111]
	ds_read_b128 v[188:191], v131 offset:2048
	ds_read_b128 v[136:139], v128 offset:2048
	v_mfma_f32_32x32x16_bf16 v[80:95], v[192:195], v[152:155], v[80:95]
	ds_read_b128 v[140:143], v128 offset:4096
	ds_read_b128 v[144:147], v128 offset:6144
	v_mfma_f32_32x32x16_bf16 v[64:79], v[208:211], v[152:155], v[64:79]
	s_add_u32 m0, s26, 0x20000
	s_nop 0
	global_load_lds_dwordx4 v[218:219], off
	v_lshl_add_u64 v[218:219], v[218:219], 0, s[6:7]
	v_mfma_f32_32x32x16_bf16 v[48:63], v[192:195], v[156:159], v[48:63]
	v_mfma_f32_32x32x16_bf16 v[32:47], v[208:211], v[156:159], v[32:47]
	v_mfma_f32_32x32x16_bf16 v[16:31], v[192:195], v[180:183], v[16:31]
	v_mfma_f32_32x32x16_bf16 v[0:15], v[208:211], v[180:183], v[0:15]
	s_add_u32 m0, s26, 0x24000
	s_nop 0
	global_load_lds_dwordx4 v[222:223], off
	v_lshl_add_u64 v[222:223], v[222:223], 0, s[6:7]
	s_sub_u32 s27, s27, 1
	s_cmp_lg_u32 s27, 0
	s_cbranch_scc1 .Lgk_ph16_loop
; #define G_LOADA(kt_) { _Pragma("unroll") for (int i = 0; i < 4; ++i) ra[i] = al(lrow + 64 * i, (kt_) * 64 + lck * 8); }
; #define G_LOADB(kt_) { _Pragma("unroll") for (int i = 0; i < 4; ++i) rb[i] = bl(lrow + 64 * i, (kt_) * 64 + lck * 8); }
; #define G_STOREA(buf_) { bf16_t* nA = sA + (buf_) * 256 * GLD; _Pragma("unroll") for (int i = 0; i < 4; ++i) *(u32x4*)(nA + (lrow + 64 * i) * GLD + lck * 8) = ra[i]; }
; #define G_STOREB(buf_) { bf16_t* nB = sB + (buf_) * 256 * GLD; _Pragma("unroll") for (int i = 0; i < 4; ++i) *(u32x4*)(nB + (lrow + 64 * i) * GLD + lck * 8) = rb[i]; }
; template <class AL, class BL, class EP>
; DI void gemm_tile256(AL al, BL bl, EP ep, int K, char* smem) {
;     ...
;   G_LOADA(0); G_LOADB(0);
;   __syncthreads();
;   G_STOREA(0); G_STOREB(0);
;   if (KT > 1) G_LOADB(1);
;   __syncthreads();
;   for (int kt = 0; kt < KT; kt += 2) {
;     G_STEP(0, kt);
;     if (kt + 1 >= KT) break;
;     G_STEP(1, kt + 1);
;   }
	s_waitcnt lgkmcnt(0)
	v_mfma_f32_32x32x16_bf16 v[112:127], v[184:187], v[132:135], v[112:127]
	ds_read_b128 v[192:195], v205
	ds_read_b128 v[148:151], v130
	v_mfma_f32_32x32x16_bf16 v[96:111], v[188:191], v[132:135], v[96:111]
	ds_read_b128 v[208:211], v205 offset:2048
	ds_read_b128 v[152:155], v130 offset:2048
	v_mfma_f32_32x32x16_bf16 v[80:95], v[184:187], v[136:139], v[80:95]
	ds_read_b128 v[156:159], v130 offset:4096
	ds_read_b128 v[180:183], v130 offset:6144
	v_mfma_f32_32x32x16_bf16 v[64:79], v[188:191], v[136:139], v[64:79]
	s_add_u32 m0, s26, 0x22000
	s_nop 0
	global_load_lds_dwordx4 v[220:221], off
	v_lshl_add_u64 v[220:221], v[220:221], 0, s[6:7]
	v_mfma_f32_32x32x16_bf16 v[48:63], v[184:187], v[140:143], v[48:63]
	v_mfma_f32_32x32x16_bf16 v[32:47], v[188:191], v[140:143], v[32:47]
	v_mfma_f32_32x32x16_bf16 v[16:31], v[184:187], v[144:147], v[16:31]
	v_mfma_f32_32x32x16_bf16 v[0:15], v[188:191], v[144:147], v[0:15]
	s_add_u32 m0, s26, 0x26000
	s_nop 0
	global_load_lds_dwordx4 v[224:225], off
	v_lshl_add_u64 v[224:225], v[224:225], 0, s[6:7]
	s_waitcnt lgkmcnt(0)
	s_waitcnt vmcnt(12)
	s_barrier
	s_waitcnt lgkmcnt(0)
	v_mfma_f32_32x32x16_bf16 v[112:127], v[192:195], v[148:151], v[112:127]
	ds_read_b128 v[184:187], v131 offset:32768
	ds_read_b128 v[132:135], v128 offset:32768
	v_mfma_f32_32x32x16_bf16 v[96:111], v[208:211], v[148:151], v[96:111]
	ds_read_b128 v[188:191], v131 offset:34816
	ds_read_b128 v[136:139], v128 offset:34816
	v_mfma_f32_32x32x16_bf16 v[80:95], v[192:195], v[152:155], v[80:95]
	ds_read_b128 v[140:143], v128 offset:36864
	ds_read_b128 v[144:147], v128 offset:38912
	v_mfma_f32_32x32x16_bf16 v[64:79], v[208:211], v[152:155], v[64:79]
	s_add_u32 m0, s26, 0x0
	s_nop 0
	global_load_lds_dwordx4 v[218:219], off
	v_lshl_add_u64 v[218:219], v[218:219], 0, s[6:7]
	v_mfma_f32_32x32x16_bf16 v[48:63], v[192:195], v[156:159], v[48:63]
	v_mfma_f32_32x32x16_bf16 v[32:47], v[208:211], v[156:159], v[32:47]
	v_mfma_f32_32x32x16_bf16 v[16:31], v[192:195], v[180:183], v[16:31]
	v_mfma_f32_32x32x16_bf16 v[0:15], v[208:211], v[180:183], v[0:15]
	s_add_u32 m0, s26, 0x4000
	s_nop 0
	global_load_lds_dwordx4 v[222:223], off
	v_lshl_add_u64 v[222:223], v[222:223], 0, s[6:7]
	s_waitcnt lgkmcnt(0)
	v_mfma_f32_32x32x16_bf16 v[112:127], v[184:187], v[132:135], v[112:127]
	ds_read_b128 v[192:195], v205 offset:32768
	ds_read_b128 v[148:151], v130 offset:32768
	v_mfma_f32_32x32x16_bf16 v[96:111], v[188:191], v[132:135], v[96:111]
	ds_read_b128 v[208:211], v205 offset:34816
	ds_read_b128 v[152:155], v130 offset:34816
	v_mfma_f32_32x32x16_bf16 v[80:95], v[184:187], v[136:139], v[80:95]
	ds_read_b128 v[156:159], v130 offset:36864
	ds_read_b128 v[180:183], v130 offset:38912
	v_mfma_f32_32x32x16_bf16 v[64:79], v[188:191], v[136:139], v[64:79]
	s_add_u32 m0, s26, 0x2000
	s_nop 0
	global_load_lds_dwordx4 v[220:221], off
	v_lshl_add_u64 v[220:221], v[220:221], 0, s[6:7]
	v_mfma_f32_32x32x16_bf16 v[48:63], v[184:187], v[140:143], v[48:63]
	v_mfma_f32_32x32x16_bf16 v[32:47], v[188:191], v[140:143], v[32:47]
	v_mfma_f32_32x32x16_bf16 v[16:31], v[184:187], v[144:147], v[16:31]
	v_mfma_f32_32x32x16_bf16 v[0:15], v[188:191], v[144:147], v[0:15]
	s_add_u32 m0, s26, 0x6000
	s_nop 0
	global_load_lds_dwordx4 v[224:225], off
	v_lshl_add_u64 v[224:225], v[224:225], 0, s[6:7]
	s_waitcnt lgkmcnt(0)
	s_waitcnt vmcnt(12)
	s_barrier
	s_waitcnt lgkmcnt(0)
	v_mfma_f32_32x32x16_bf16 v[112:127], v[192:195], v[148:151], v[112:127]
	ds_read_b128 v[184:187], v212
	ds_read_b128 v[132:135], v206
	v_mfma_f32_32x32x16_bf16 v[96:111], v[208:211], v[148:151], v[96:111]
	ds_read_b128 v[188:191], v212 offset:2048
	ds_read_b128 v[136:139], v206 offset:2048
	v_mfma_f32_32x32x16_bf16 v[80:95], v[192:195], v[152:155], v[80:95]
	ds_read_b128 v[140:143], v206 offset:4096
	ds_read_b128 v[144:147], v206 offset:6144
	v_mfma_f32_32x32x16_bf16 v[64:79], v[208:211], v[152:155], v[64:79]
	s_add_u32 m0, s26, 0x8000
	s_nop 0
	global_load_lds_dwordx4 v[218:219], off
	v_lshl_add_u64 v[218:219], v[218:219], 0, s[6:7]
	v_mfma_f32_32x32x16_bf16 v[48:63], v[192:195], v[156:159], v[48:63]
	v_mfma_f32_32x32x16_bf16 v[32:47], v[208:211], v[156:159], v[32:47]
	v_mfma_f32_32x32x16_bf16 v[16:31], v[192:195], v[180:183], v[16:31]
	v_mfma_f32_32x32x16_bf16 v[0:15], v[208:211], v[180:183], v[0:15]
	s_add_u32 m0, s26, 0xc000
	s_nop 0
	global_load_lds_dwordx4 v[222:223], off
	v_lshl_add_u64 v[222:223], v[222:223], 0, s[6:7]
	s_waitcnt lgkmcnt(0)
	v_mfma_f32_32x32x16_bf16 v[112:127], v[184:187], v[132:135], v[112:127]
	ds_read_b128 v[192:195], v213
	ds_read_b128 v[148:151], v207
	v_mfma_f32_32x32x16_bf16 v[96:111], v[188:191], v[132:135], v[96:111]
	ds_read_b128 v[208:211], v213 offset:2048
	ds_read_b128 v[152:155], v207 offset:2048
	v_mfma_f32_32x32x16_bf16 v[80:95], v[184:187], v[136:139], v[80:95]
	ds_read_b128 v[156:159], v207 offset:4096
	ds_read_b128 v[180:183], v207 offset:6144
	v_mfma_f32_32x32x16_bf16 v[64:79], v[188:191], v[136:139], v[64:79]
	s_add_u32 m0, s26, 0xa000
	s_nop 0
	global_load_lds_dwordx4 v[220:221], off
	v_lshl_add_u64 v[220:221], v[220:221], 0, s[6:7]
	v_mfma_f32_32x32x16_bf16 v[48:63], v[184:187], v[140:143], v[48:63]
	v_mfma_f32_32x32x16_bf16 v[32:47], v[188:191], v[140:143], v[32:47]
	v_mfma_f32_32x32x16_bf16 v[16:31], v[184:187], v[144:147], v[16:31]
	v_mfma_f32_32x32x16_bf16 v[0:15], v[188:191], v[144:147], v[0:15]
	s_add_u32 m0, s26, 0xe000
	s_nop 0
	global_load_lds_dwordx4 v[224:225], off
	v_lshl_add_u64 v[224:225], v[224:225], 0, s[6:7]
	s_waitcnt lgkmcnt(0)
	s_waitcnt vmcnt(12)
	s_barrier
; #define G_LOADA(kt_) { _Pragma("unroll") for (int i = 0; i < 4; ++i) ra[i] = al(lrow + 64 * i, (kt_) * 64 + lck * 8); }
; #define G_LOADB(kt_) { _Pragma("unroll") for (int i = 0; i < 4; ++i) rb[i] = bl(lrow + 64 * i, (kt_) * 64 + lck * 8); }
; #define G_STOREA(buf_) { bf16_t* nA = sA + (buf_) * 256 * GLD; _Pragma("unroll") for (int i = 0; i < 4; ++i) *(u32x4*)(nA + (lrow + 64 * i) * GLD + lck * 8) = ra[i]; }
; #define G_STOREB(buf_) { bf16_t* nB = sB + (buf_) * 256 * GLD; _Pragma("unroll") for (int i = 0; i < 4; ++i) *(u32x4*)(nB + (lrow + 64 * i) * GLD + lck * 8) = rb[i]; }
; template <class AL, class BL, class EP>
; DI void gemm_tile256(AL al, BL bl, EP ep, int K, char* smem) {
;     ...
;   G_LOADA(0); G_LOADB(0);
;   __syncthreads();
;   G_STOREA(0); G_STOREB(0);
;   if (KT > 1) G_LOADB(1);
;   __syncthreads();
;   for (int kt = 0; kt < KT; kt += 2) {
;     G_STEP(0, kt);
;     if (kt + 1 >= KT) break;
;     G_STEP(1, kt + 1);
;   }
	s_waitcnt lgkmcnt(0)
	v_mfma_f32_32x32x16_bf16 v[112:127], v[192:195], v[148:151], v[112:127]
	ds_read_b128 v[184:187], v212 offset:32768
	ds_read_b128 v[132:135], v206 offset:32768
	v_mfma_f32_32x32x16_bf16 v[96:111], v[208:211], v[148:151], v[96:111]
	ds_read_b128 v[188:191], v212 offset:34816
	ds_read_b128 v[136:139], v206 offset:34816
	v_mfma_f32_32x32x16_bf16 v[80:95], v[192:195], v[152:155], v[80:95]
	ds_read_b128 v[140:143], v206 offset:36864
	ds_read_b128 v[144:147], v206 offset:38912
	v_mfma_f32_32x32x16_bf16 v[64:79], v[208:211], v[152:155], v[64:79]
	s_add_u32 m0, s26, 0x10000
	s_nop 0
	global_load_lds_dwordx4 v[218:219], off
	v_lshl_add_u64 v[218:219], v[218:219], 0, s[6:7]
	v_mfma_f32_32x32x16_bf16 v[48:63], v[192:195], v[156:159], v[48:63]
	v_mfma_f32_32x32x16_bf16 v[32:47], v[208:211], v[156:159], v[32:47]
	v_mfma_f32_32x32x16_bf16 v[16:31], v[192:195], v[180:183], v[16:31]
	v_mfma_f32_32x32x16_bf16 v[0:15], v[208:211], v[180:183], v[0:15]
	s_add_u32 m0, s26, 0x14000
	s_nop 0
	global_load_lds_dwordx4 v[222:223], off
	v_lshl_add_u64 v[222:223], v[222:223], 0, s[6:7]
	s_waitcnt lgkmcnt(0)
	v_mfma_f32_32x32x16_bf16 v[112:127], v[184:187], v[132:135], v[112:127]
	ds_read_b128 v[192:195], v213 offset:32768
	ds_read_b128 v[148:151], v207 offset:32768
	v_mfma_f32_32x32x16_bf16 v[96:111], v[188:191], v[132:135], v[96:111]
	ds_read_b128 v[208:211], v213 offset:34816
	ds_read_b128 v[152:155], v207 offset:34816
	v_mfma_f32_32x32x16_bf16 v[80:95], v[184:187], v[136:139], v[80:95]
	ds_read_b128 v[156:159], v207 offset:36864
	ds_read_b128 v[180:183], v207 offset:38912
	v_mfma_f32_32x32x16_bf16 v[64:79], v[188:191], v[136:139], v[64:79]
	s_add_u32 m0, s26, 0x12000
	s_nop 0
	global_load_lds_dwordx4 v[220:221], off
	v_lshl_add_u64 v[220:221], v[220:221], 0, s[6:7]
	v_mfma_f32_32x32x16_bf16 v[48:63], v[184:187], v[140:143], v[48:63]
	v_mfma_f32_32x32x16_bf16 v[32:47], v[188:191], v[140:143], v[32:47]
	v_mfma_f32_32x32x16_bf16 v[16:31], v[184:187], v[144:147], v[16:31]
	v_mfma_f32_32x32x16_bf16 v[0:15], v[188:191], v[144:147], v[0:15]
	s_add_u32 m0, s26, 0x16000
	s_nop 0
	global_load_lds_dwordx4 v[224:225], off
	v_lshl_add_u64 v[224:225], v[224:225], 0, s[6:7]
	s_waitcnt lgkmcnt(0)
	s_waitcnt vmcnt(12)
	s_barrier
	s_waitcnt lgkmcnt(0)
	v_mfma_f32_32x32x16_bf16 v[112:127], v[192:195], v[148:151], v[112:127]
	ds_read_b128 v[184:187], v216
	ds_read_b128 v[132:135], v214
	v_mfma_f32_32x32x16_bf16 v[96:111], v[208:211], v[148:151], v[96:111]
	ds_read_b128 v[188:191], v216 offset:2048
	ds_read_b128 v[136:139], v214 offset:2048
	v_mfma_f32_32x32x16_bf16 v[80:95], v[192:195], v[152:155], v[80:95]
	ds_read_b128 v[140:143], v214 offset:4096
	ds_read_b128 v[144:147], v214 offset:6144
	v_mfma_f32_32x32x16_bf16 v[64:79], v[208:211], v[152:155], v[64:79]
	v_mfma_f32_32x32x16_bf16 v[48:63], v[192:195], v[156:159], v[48:63]
	v_mfma_f32_32x32x16_bf16 v[32:47], v[208:211], v[156:159], v[32:47]
	v_mfma_f32_32x32x16_bf16 v[16:31], v[192:195], v[180:183], v[16:31]
	v_mfma_f32_32x32x16_bf16 v[0:15], v[208:211], v[180:183], v[0:15]
	s_waitcnt lgkmcnt(0)
	v_mfma_f32_32x32x16_bf16 v[112:127], v[184:187], v[132:135], v[112:127]
	ds_read_b128 v[192:195], v217
	ds_read_b128 v[148:151], v215
	v_mfma_f32_32x32x16_bf16 v[96:111], v[188:191], v[132:135], v[96:111]
	ds_read_b128 v[208:211], v217 offset:2048
	ds_read_b128 v[152:155], v215 offset:2048
	v_mfma_f32_32x32x16_bf16 v[80:95], v[184:187], v[136:139], v[80:95]
	ds_read_b128 v[156:159], v215 offset:4096
	ds_read_b128 v[180:183], v215 offset:6144
	v_mfma_f32_32x32x16_bf16 v[64:79], v[188:191], v[136:139], v[64:79]
	v_mfma_f32_32x32x16_bf16 v[48:63], v[184:187], v[140:143], v[48:63]
	v_mfma_f32_32x32x16_bf16 v[32:47], v[188:191], v[140:143], v[32:47]
	v_mfma_f32_32x32x16_bf16 v[16:31], v[184:187], v[144:147], v[16:31]
	v_mfma_f32_32x32x16_bf16 v[0:15], v[188:191], v[144:147], v[0:15]
	s_waitcnt lgkmcnt(0)
	s_waitcnt vmcnt(8)
	s_barrier
	s_waitcnt lgkmcnt(0)
	v_mfma_f32_32x32x16_bf16 v[112:127], v[192:195], v[148:151], v[112:127]
	ds_read_b128 v[184:187], v131
	ds_read_b128 v[132:135], v128
	v_mfma_f32_32x32x16_bf16 v[96:111], v[208:211], v[148:151], v[96:111]
	ds_read_b128 v[188:191], v131 offset:2048
	ds_read_b128 v[136:139], v128 offset:2048
	v_mfma_f32_32x32x16_bf16 v[80:95], v[192:195], v[152:155], v[80:95]
	ds_read_b128 v[140:143], v128 offset:4096
	ds_read_b128 v[144:147], v128 offset:6144
	v_mfma_f32_32x32x16_bf16 v[64:79], v[208:211], v[152:155], v[64:79]
	v_mfma_f32_32x32x16_bf16 v[48:63], v[192:195], v[156:159], v[48:63]
	v_mfma_f32_32x32x16_bf16 v[32:47], v[208:211], v[156:159], v[32:47]
	v_mfma_f32_32x32x16_bf16 v[16:31], v[192:195], v[180:183], v[16:31]
	v_mfma_f32_32x32x16_bf16 v[0:15], v[208:211], v[180:183], v[0:15]
	s_waitcnt lgkmcnt(0)
	v_mfma_f32_32x32x16_bf16 v[112:127], v[184:187], v[132:135], v[112:127]
	ds_read_b128 v[192:195], v205
	ds_read_b128 v[148:151], v130
	v_mfma_f32_32x32x16_bf16 v[96:111], v[188:191], v[132:135], v[96:111]
	ds_read_b128 v[208:211], v205 offset:2048
	ds_read_b128 v[152:155], v130 offset:2048
	v_mfma_f32_32x32x16_bf16 v[80:95], v[184:187], v[136:139], v[80:95]
	ds_read_b128 v[156:159], v130 offset:4096
	ds_read_b128 v[180:183], v130 offset:6144
	v_mfma_f32_32x32x16_bf16 v[64:79], v[188:191], v[136:139], v[64:79]
	v_mfma_f32_32x32x16_bf16 v[48:63], v[184:187], v[140:143], v[48:63]
	v_mfma_f32_32x32x16_bf16 v[32:47], v[188:191], v[140:143], v[32:47]
	v_mfma_f32_32x32x16_bf16 v[16:31], v[184:187], v[144:147], v[16:31]
	v_mfma_f32_32x32x16_bf16 v[0:15], v[188:191], v[144:147], v[0:15]
	s_waitcnt lgkmcnt(0)
	s_waitcnt vmcnt(4)
	s_barrier
; #define G_LOADA(kt_) { _Pragma("unroll") for (int i = 0; i < 4; ++i) ra[i] = al(lrow + 64 * i, (kt_) * 64 + lck * 8); }
; #define G_LOADB(kt_) { _Pragma("unroll") for (int i = 0; i < 4; ++i) rb[i] = bl(lrow + 64 * i, (kt_) * 64 + lck * 8); }
; #define G_STOREA(buf_) { bf16_t* nA = sA + (buf_) * 256 * GLD; _Pragma("unroll") for (int i = 0; i < 4; ++i) *(u32x4*)(nA + (lrow + 64 * i) * GLD + lck * 8) = ra[i]; }
; #define G_STOREB(buf_) { bf16_t* nB = sB + (buf_) * 256 * GLD; _Pragma("unroll") for (int i = 0; i < 4; ++i) *(u32x4*)(nB + (lrow + 64 * i) * GLD + lck * 8) = rb[i]; }
; template <class AL, class BL, class EP>
; DI void gemm_tile256(AL al, BL bl, EP ep, int K, char* smem) {
;     ...
;   G_LOADA(0); G_LOADB(0);
;   __syncthreads();
;   G_STOREA(0); G_STOREB(0);
;   if (KT > 1) G_LOADB(1);
;   __syncthreads();
;   for (int kt = 0; kt < KT; kt += 2) {
;     G_STEP(0, kt);
;     if (kt + 1 >= KT) break;
;     G_STEP(1, kt + 1);
;   }
;     ...
;     __syncthreads();
	s_waitcnt lgkmcnt(0)
	v_mfma_f32_32x32x16_bf16 v[112:127], v[192:195], v[148:151], v[112:127]
	ds_read_b128 v[184:187], v131 offset:32768
	ds_read_b128 v[132:135], v128 offset:32768
	v_mfma_f32_32x32x16_bf16 v[96:111], v[208:211], v[148:151], v[96:111]
	ds_read_b128 v[188:191], v131 offset:34816
	ds_read_b128 v[136:139], v128 offset:34816
	v_mfma_f32_32x32x16_bf16 v[80:95], v[192:195], v[152:155], v[80:95]
	ds_read_b128 v[140:143], v128 offset:36864
	ds_read_b128 v[144:147], v128 offset:38912
	v_mfma_f32_32x32x16_bf16 v[64:79], v[208:211], v[152:155], v[64:79]
	v_mfma_f32_32x32x16_bf16 v[48:63], v[192:195], v[156:159], v[48:63]
	v_mfma_f32_32x32x16_bf16 v[32:47], v[208:211], v[156:159], v[32:47]
	v_mfma_f32_32x32x16_bf16 v[16:31], v[192:195], v[180:183], v[16:31]
	v_mfma_f32_32x32x16_bf16 v[0:15], v[208:211], v[180:183], v[0:15]
	s_waitcnt lgkmcnt(0)
	v_mfma_f32_32x32x16_bf16 v[112:127], v[184:187], v[132:135], v[112:127]
	ds_read_b128 v[192:195], v205 offset:32768
	ds_read_b128 v[148:151], v130 offset:32768
	v_mfma_f32_32x32x16_bf16 v[96:111], v[188:191], v[132:135], v[96:111]
	ds_read_b128 v[208:211], v205 offset:34816
	ds_read_b128 v[152:155], v130 offset:34816
	v_mfma_f32_32x32x16_bf16 v[80:95], v[184:187], v[136:139], v[80:95]
	ds_read_b128 v[156:159], v130 offset:36864
	ds_read_b128 v[180:183], v130 offset:38912
	v_mfma_f32_32x32x16_bf16 v[64:79], v[188:191], v[136:139], v[64:79]
	v_mfma_f32_32x32x16_bf16 v[48:63], v[184:187], v[140:143], v[48:63]
	v_mfma_f32_32x32x16_bf16 v[32:47], v[188:191], v[140:143], v[32:47]
	v_mfma_f32_32x32x16_bf16 v[16:31], v[184:187], v[144:147], v[16:31]
	v_mfma_f32_32x32x16_bf16 v[0:15], v[188:191], v[144:147], v[0:15]
	s_waitcnt lgkmcnt(0)
	s_waitcnt vmcnt(0)
	s_barrier
	s_waitcnt lgkmcnt(0)
	v_mfma_f32_32x32x16_bf16 v[112:127], v[192:195], v[148:151], v[112:127]
	ds_read_b128 v[184:187], v212
	ds_read_b128 v[132:135], v206
	v_mfma_f32_32x32x16_bf16 v[96:111], v[208:211], v[148:151], v[96:111]
	ds_read_b128 v[188:191], v212 offset:2048
	ds_read_b128 v[136:139], v206 offset:2048
	v_mfma_f32_32x32x16_bf16 v[80:95], v[192:195], v[152:155], v[80:95]
	ds_read_b128 v[140:143], v206 offset:4096
	ds_read_b128 v[144:147], v206 offset:6144
	v_mfma_f32_32x32x16_bf16 v[64:79], v[208:211], v[152:155], v[64:79]
	v_mfma_f32_32x32x16_bf16 v[48:63], v[192:195], v[156:159], v[48:63]
	v_mfma_f32_32x32x16_bf16 v[32:47], v[208:211], v[156:159], v[32:47]
	v_mfma_f32_32x32x16_bf16 v[16:31], v[192:195], v[180:183], v[16:31]
	v_mfma_f32_32x32x16_bf16 v[0:15], v[208:211], v[180:183], v[0:15]
	s_waitcnt lgkmcnt(0)
	v_mfma_f32_32x32x16_bf16 v[112:127], v[184:187], v[132:135], v[112:127]
	ds_read_b128 v[192:195], v213
	ds_read_b128 v[148:151], v207
	v_mfma_f32_32x32x16_bf16 v[96:111], v[188:191], v[132:135], v[96:111]
	ds_read_b128 v[208:211], v213 offset:2048
	ds_read_b128 v[152:155], v207 offset:2048
	v_mfma_f32_32x32x16_bf16 v[80:95], v[184:187], v[136:139], v[80:95]
	ds_read_b128 v[156:159], v207 offset:4096
	ds_read_b128 v[180:183], v207 offset:6144
	v_mfma_f32_32x32x16_bf16 v[64:79], v[188:191], v[136:139], v[64:79]
	v_mfma_f32_32x32x16_bf16 v[48:63], v[184:187], v[140:143], v[48:63]
	v_mfma_f32_32x32x16_bf16 v[32:47], v[188:191], v[140:143], v[32:47]
	v_mfma_f32_32x32x16_bf16 v[16:31], v[184:187], v[144:147], v[16:31]
	v_mfma_f32_32x32x16_bf16 v[0:15], v[188:191], v[144:147], v[0:15]
	s_waitcnt lgkmcnt(0)
	s_waitcnt lgkmcnt(0)
	v_mfma_f32_32x32x16_bf16 v[112:127], v[192:195], v[148:151], v[112:127]
	v_mfma_f32_32x32x16_bf16 v[96:111], v[208:211], v[148:151], v[96:111]
	v_mfma_f32_32x32x16_bf16 v[80:95], v[192:195], v[152:155], v[80:95]
	v_mfma_f32_32x32x16_bf16 v[64:79], v[208:211], v[152:155], v[64:79]
	v_mfma_f32_32x32x16_bf16 v[48:63], v[192:195], v[156:159], v[48:63]
	v_mfma_f32_32x32x16_bf16 v[32:47], v[208:211], v[156:159], v[32:47]
	v_mfma_f32_32x32x16_bf16 v[16:31], v[192:195], v[180:183], v[16:31]
	v_mfma_f32_32x32x16_bf16 v[0:15], v[208:211], v[180:183], v[0:15]
	s_nop 15
	s_nop 3
	s_barrier
	s_branch .LBB0_1268
